# P5 epilogue: tanh-gelu polynomial and 1+exp in packed f32 (v_pk_mul/fma/add), same operation order
# speedup vs baseline: 1.0056x; 1.0055x over previous
; #define LAS __attribute__((address_space(3)))
;     __device__ __forceinline__ void operator()(const f32x4 (&acc)[2][2][4][2], const Unit& u, int wr, int wc, int fr, int fq, LAS unsigned char* hb) const {
;         constexpr int H = 2, NCH = 128;
;         int chl = wc * 32 + 8 * fq; asm volatile("" : "+v"(chl), "+v"(fr));
;         const int R0 = 254 * u.pm - 2; const int ch = u.pn * HALF + chl;
;         if (fr >= 16 - H) {
; #pragma unroll
;             for (int ai = 0; ai < 2; ++ai)
; #pragma unroll
;                 for (int m = 0; m < 4; ++m) { const int q = 8 * ai + 4 * wr + m;
;                     LAS f32x4* hw = (LAS f32x4*)(hb + ((q * H + fr - (16 - H)) * NCH + chl) * 4); hw[0] = acc[ai][0][m][0]; hw[1] = acc[ai][0][m][1]; }
;         }
;         asm volatile("s_waitcnt lgkmcnt(0)" ::: "memory"); __builtin_amdgcn_s_barrier(); asm volatile("" ::: "memory");
;         const int hr1 = H - 1, hr2 = (H - 2 + fr) < (H - 1) ? (H - 2 + fr) : (H - 1);
; #pragma unroll
;         for (int n = 0; n < 2; ++n) { asm volatile("" ::: "memory");
;             const int c4 = ch + 4 * n;
;             const f32x4 w0 = *(const f32x4*)(cw + 0 * DFF + c4), w1 = *(const f32x4*)(cw + 1 * DFF + c4), w2 = *(const f32x4*)(cw + 2 * DFF + c4), bs = *(const f32x4*)(cb + c4);
; #pragma unroll
;             for (int ai = 0; ai < 2; ++ai)
; #pragma unroll
;                 for (int m = 0; m < 4; ++m) { const int q = 8 * ai + 4 * wr + m, prev = q > 0 ? q - 1 : 0; const int lr = ai * HALF + wr * 64 + m * 16 + fr, R = R0 + lr;
;                     const int Rc = R < 0 ? 0 : R; const int b = Rc / LL, p = Rc - b * LL;
;                     const LAS unsigned char* hp = hb + (prev * H * NCH + chl + 4 * n) * 4;
;                     const f32x4 h1 = *(const LAS f32x4*)(hp + hr1 * NCH * 4), h2 = *(const LAS f32x4*)(hp + hr2 * NCH * 4);
;                     const f32x4 gv = acc[ai][0][m][n], uv = acc[ai][1][m][n];
;                     float o[4];
; #pragma unroll
;                     for (int j = 0; j < 4; ++j) { const float g = gv[j];
;                         float g1 = dpp_row_shr<1>(h1[j], g), g2 = dpp_row_shr<2>(h2[j], g);
;                         g1 = p >= 1 ? g1 : 0.f; g2 = p >= 2 ? g2 : 0.f;
;                         const float v = bs[j] + w2[j] * g + w1[j] * g1 + w0[j] * g2;
;                         const float a = v + 0.044715f * v * v * v;
.LBB0_884:
	s_mov_b32 s98, 0x3d372713
	s_mov_b32 s100, 0xc0135761
	v_mov_b32_e32 v116, v183
	v_mov_b32_e32 v144, v153
	s_nop 0
	v_cmp_gt_i32_e32 vcc, 14, v144
	v_lshlrev_b32_e32 v188, 2, v116
	s_and_saveexec_b64 s[6:7], vcc
	s_xor_b64 s[6:7], exec, s[6:7]
	v_lshlrev_b32_e32 v188, 2, v116
	s_andn2_saveexec_b64 s[6:7], s[6:7]
	s_cbranch_execz .LBB0_888
	v_lshlrev_b32_e32 v117, 9, v144
	v_add3_u32 v117, s50, v117, v188
	v_add_u32_e32 v118, 0xffffe400, v117
	ds_write_b128 v118, v[140:143]
	v_add_u32_e32 v118, 0xffffe410, v117
	ds_write_b128 v118, v[64:67]
	v_add_u32_e32 v118, 0xffffe800, v117
	ds_write_b128 v118, v[124:127]
	v_add_u32_e32 v118, 0xffffe810, v117
	ds_write_b128 v118, v[52:55]
	v_add_u32_e32 v118, 0xffffec00, v117
	ds_write_b128 v118, v[108:111]
	v_add_u32_e32 v118, 0xffffec10, v117
	ds_write_b128 v118, v[44:47]
	v_add_u32_e32 v118, 0xfffff000, v117
	ds_write_b128 v118, v[100:103]
	v_add_u32_e32 v118, 0xfffff010, v117
	ds_write_b128 v118, v[36:39]
	ds_write_b128 v117, v[92:95] offset:1024
	ds_write_b128 v117, v[28:31] offset:1040
	ds_write_b128 v117, v[84:87] offset:2048
	ds_write_b128 v117, v[20:23] offset:2064
	ds_write_b128 v117, v[76:79] offset:3072
	ds_write_b128 v117, v[12:15] offset:3088
	ds_write_b128 v117, v[68:71] offset:4096
	ds_write_b128 v117, v[4:7] offset:4112
.LBB0_888:
	s_or_b64 exec, exec, s[6:7]
	v_readlane_b32 s72, v237, 30
	v_lshl_add_u32 v170, s40, 7, v116
	v_readlane_b32 s76, v237, 34
	v_readlane_b32 s77, v237, 35
	v_readlane_b32 s78, v237, 36
	v_readlane_b32 s79, v237, 37
	v_readlane_b32 s80, v237, 38
	v_readlane_b32 s81, v237, 39
	v_readlane_b32 s82, v237, 40
	v_readlane_b32 s83, v237, 41
	v_ashrrev_i32_e32 v171, 31, v170
	v_readlane_b32 s76, v237, 0
	s_waitcnt lgkmcnt(0)
	s_barrier
	v_lshlrev_b64 v[132:133], 2, v[170:171]
	v_readlane_b32 s86, v237, 44
	v_readlane_b32 s87, v237, 45
	v_readlane_b32 s77, v237, 1
	v_lshl_add_u64 v[176:177], s[18:19], 0, v[132:133]
	v_lshl_add_u64 v[172:173], s[86:87], 0, v[132:133]
	v_lshl_add_u64 v[178:179], s[76:77], 0, v[132:133]
	v_lshl_add_u64 v[174:175], s[16:17], 0, v[132:133]
	global_load_dwordx4 v[116:119], v[172:173], off
	global_load_dwordx4 v[120:123], v[174:175], off
	global_load_dwordx4 v[128:131], v[176:177], off
	global_load_dwordx4 v[132:135], v[178:179], off
	s_mul_i32 s21, s30, 0xfe
	s_add_i32 s21, s21, -2
	v_add_u32_e32 v190, s47, v144
	v_min_i32_e32 v145, 1, v144
	v_add_u32_e32 v189, s21, v190
	v_add_u32_e32 v191, 0xfffffc00, v188
	v_lshlrev_b32_e32 v187, 9, v145
	v_max_i32_e32 v192, 0, v189
	v_add_u32_e32 v144, s51, v191
	v_mul_hi_u32 v193, v192, s64
	v_add_u32_e32 v145, v144, v187
	ds_read_b128 v[148:151], v144 offset:512
	ds_read_b128 v[144:147], v145
	v_lshrrev_b32_e32 v193, 11, v193
	v_mul_i32_i24_e32 v194, 0xffffeff0, v193
	v_add_u32_e32 v192, v194, v192
	v_cmp_lt_i32_e32 vcc, 1, v190
	v_cmp_lt_i32_e64 s[8:9], 15, v192
	v_cmp_gt_i32_e64 s[6:7], s65, v189
	s_and_b64 s[8:9], vcc, s[8:9]
	s_waitcnt lgkmcnt(0)
	v_mov_b32_dpp v148, v140 row_shr:1 row_mask:0xf bank_mask:0xf
	v_mov_b32_dpp v144, v140 row_shr:2 row_mask:0xf bank_mask:0xf
	v_mov_b32_dpp v149, v141 row_shr:1 row_mask:0xf bank_mask:0xf
	v_mov_b32_dpp v145, v141 row_shr:2 row_mask:0xf bank_mask:0xf
	v_mov_b32_dpp v150, v142 row_shr:1 row_mask:0xf bank_mask:0xf
	v_mov_b32_dpp v146, v142 row_shr:2 row_mask:0xf bank_mask:0xf
	v_mov_b32_dpp v151, v143 row_shr:1 row_mask:0xf bank_mask:0xf
	v_mov_b32_dpp v147, v143 row_shr:2 row_mask:0xf bank_mask:0xf
	s_and_b64 s[26:27], s[8:9], s[6:7]
	v_lshl_add_u32 v189, v193, 12, v192
	v_readlane_b32 s73, v237, 31
	v_readlane_b32 s74, v237, 32
	v_readlane_b32 s75, v237, 33
	v_readlane_b32 s84, v237, 42
	v_readlane_b32 s85, v237, 43
	v_readlane_b32 s78, v237, 2
	v_readlane_b32 s79, v237, 3
	v_readlane_b32 s80, v237, 4
	v_readlane_b32 s81, v237, 5
	v_readlane_b32 s82, v237, 6
	v_readlane_b32 s83, v237, 7
	s_waitcnt vmcnt(0)
	s_and_saveexec_b64 s[6:7], s[26:27]
	s_cbranch_execz .LBB0_890
	v_pk_fma_f32 v[140:141], v[140:141], v[128:129], v[132:133]
	v_pk_fma_f32 v[142:143], v[142:143], v[130:131], v[134:135]
	v_pk_fma_f32 v[140:141], v[120:121], v[148:149], v[140:141]
	v_pk_fma_f32 v[142:143], v[122:123], v[150:151], v[142:143]
	v_pk_fma_f32 v[140:141], v[116:117], v[144:145], v[140:141]
	v_pk_fma_f32 v[142:143], v[118:119], v[146:147], v[142:143]
	v_pk_mul_f32 v[144:145], v[140:141], s[98:99] op_sel_hi:[1,0]
	v_pk_mul_f32 v[146:147], v[142:143], s[98:99] op_sel_hi:[1,0]
	v_pk_mul_f32 v[144:145], v[140:141], v[144:145]
	v_pk_mul_f32 v[146:147], v[142:143], v[146:147]
	v_pk_fma_f32 v[144:145], v[140:141], v[144:145], v[140:141]
	v_pk_fma_f32 v[146:147], v[142:143], v[146:147], v[142:143]
	v_pk_mul_f32 v[144:145], v[144:145], s[100:101] op_sel_hi:[1,0]
	v_pk_mul_f32 v[146:147], v[146:147], s[100:101] op_sel_hi:[1,0]
	v_exp_f32_e32 v144, v144
	v_exp_f32_e32 v145, v145
	v_exp_f32_e32 v146, v146
	v_exp_f32_e32 v147, v147
	v_pk_add_f32 v[144:145], v[144:145], 1.0 op_sel_hi:[1,0]
	v_pk_add_f32 v[146:147], v[146:147], 1.0 op_sel_hi:[1,0]
	v_rcp_f32_e32 v144, v144
	v_rcp_f32_e32 v145, v145
	v_rcp_f32_e32 v146, v146
	v_rcp_f32_e32 v147, v147
	s_nop 0
	v_pk_mul_f32 v[140:141], v[140:141], v[144:145]
	v_pk_mul_f32 v[136:137], v[136:137], v[140:141]
	v_pk_mul_f32 v[140:141], v[142:143], v[146:147]
	v_pk_mul_f32 v[138:139], v[138:139], v[140:141]
	v_cvt_pk_bf16_f32 v196, v136, v137
	v_cvt_pk_bf16_f32 v197, v138, v139
; #define LAS __attribute__((address_space(3)))
; __device__ __forceinline__ unsigned pk2e(float lo, float hi) { typedef __bf16 b2 __attribute__((ext_vector_type(2))); b2 v; v.x = (__bf16)lo; v.y = (__bf16)hi; return __builtin_bit_cast(unsigned, v); }
; __device__ __forceinline__ float ex2(float x) { return __builtin_amdgcn_exp2f(x); }
;     __device__ __forceinline__ void operator()(const f32x4 (&acc)[2][2][4][2], const Unit& u, int wr, int wc, int fr, int fq, LAS unsigned char* hb) const {
;     ...
;                 for (int m = 0; m < 4; ++m) { const int q = 8 * ai + 4 * wr + m, prev = q > 0 ? q - 1 : 0; const int lr = ai * HALF + wr * 64 + m * 16 + fr, R = R0 + lr;
;                     const int Rc = R < 0 ? 0 : R; const int b = Rc / LL, p = Rc - b * LL;
;                     const LAS unsigned char* hp = hb + (prev * H * NCH + chl + 4 * n) * 4;
;                     const f32x4 h1 = *(const LAS f32x4*)(hp + hr1 * NCH * 4), h2 = *(const LAS f32x4*)(hp + hr2 * NCH * 4);
;                     const f32x4 gv = acc[ai][0][m][n], uv = acc[ai][1][m][n];
;                     float o[4];
; #pragma unroll
;                     for (int j = 0; j < 4; ++j) { const float g = gv[j];
;                         float g1 = dpp_row_shr<1>(h1[j], g), g2 = dpp_row_shr<2>(h2[j], g);
;                         g1 = p >= 1 ? g1 : 0.f; g2 = p >= 2 ? g2 : 0.f;
;                         const float v = bs[j] + w2[j] * g + w1[j] * g1 + w0[j] * g2;
;                         const float a = v + 0.044715f * v * v * v;
;                         const float ge = v * __builtin_amdgcn_rcpf(1.f + ex2(-2.f * 0.7978845608028654f * 1.4426950408889634f * a));
;                         o[j] = ge * uv[j]; }
;                     if (lr >= H && R < TT && p >= NMETA) { u32x2 w; w.x = pk2e(o[0], o[1]); w.y = pk2e(o[2], o[3]);
;                         *(u32x2*)(ACT + ((size_t)b * SEQ + p - NMETA) * DFF + c4) = w; } }
.LBB0_890:
	s_or_b64 exec, exec, s[6:7]
	v_add_u32_e32 v144, 16, v190
	v_add_u32_e32 v145, s21, v144
	v_max_i32_e32 v146, 0, v145
	v_add_u32_e32 v136, s52, v191
	v_mul_hi_u32 v147, v146, s64
	v_add_u32_e32 v137, v136, v187
	ds_read_b128 v[140:143], v136 offset:512
	ds_read_b128 v[136:139], v137
	v_lshrrev_b32_e32 v147, 11, v147
	v_mul_i32_i24_e32 v148, 0xffffeff0, v147
	v_add_u32_e32 v146, v148, v146
	v_cmp_lt_i32_e32 vcc, 1, v144
	v_cmp_lt_i32_e64 s[8:9], 15, v146
	v_cmp_gt_i32_e64 s[6:7], s65, v145
	s_and_b64 s[8:9], vcc, s[8:9]
	s_waitcnt lgkmcnt(0)
	v_mov_b32_dpp v140, v124 row_shr:1 row_mask:0xf bank_mask:0xf
	v_mov_b32_dpp v136, v124 row_shr:2 row_mask:0xf bank_mask:0xf
	v_mov_b32_dpp v141, v125 row_shr:1 row_mask:0xf bank_mask:0xf
	v_mov_b32_dpp v137, v125 row_shr:2 row_mask:0xf bank_mask:0xf
	v_mov_b32_dpp v142, v126 row_shr:1 row_mask:0xf bank_mask:0xf
	v_mov_b32_dpp v138, v126 row_shr:2 row_mask:0xf bank_mask:0xf
	v_mov_b32_dpp v143, v127 row_shr:1 row_mask:0xf bank_mask:0xf
	v_mov_b32_dpp v139, v127 row_shr:2 row_mask:0xf bank_mask:0xf
	s_and_b64 s[28:29], s[8:9], s[6:7]
	v_lshl_add_u32 v144, v147, 12, v146
	s_and_saveexec_b64 s[6:7], s[28:29]
	s_cbranch_execz .LBB0_892
	v_pk_fma_f32 v[124:125], v[124:125], v[128:129], v[132:133]
	v_pk_fma_f32 v[126:127], v[126:127], v[130:131], v[134:135]
	v_pk_fma_f32 v[124:125], v[120:121], v[140:141], v[124:125]
	v_pk_fma_f32 v[126:127], v[122:123], v[142:143], v[126:127]
	v_pk_fma_f32 v[124:125], v[116:117], v[136:137], v[124:125]
	v_pk_fma_f32 v[126:127], v[118:119], v[138:139], v[126:127]
	v_pk_mul_f32 v[136:137], v[124:125], s[98:99] op_sel_hi:[1,0]
	v_pk_mul_f32 v[138:139], v[126:127], s[98:99] op_sel_hi:[1,0]
	v_pk_mul_f32 v[136:137], v[124:125], v[136:137]
	v_pk_mul_f32 v[138:139], v[126:127], v[138:139]
	v_pk_fma_f32 v[136:137], v[124:125], v[136:137], v[124:125]
	v_pk_fma_f32 v[138:139], v[126:127], v[138:139], v[126:127]
	v_pk_mul_f32 v[136:137], v[136:137], s[100:101] op_sel_hi:[1,0]
	v_pk_mul_f32 v[138:139], v[138:139], s[100:101] op_sel_hi:[1,0]
	v_exp_f32_e32 v136, v136
	v_exp_f32_e32 v137, v137
	v_exp_f32_e32 v138, v138
	v_exp_f32_e32 v139, v139
	v_pk_add_f32 v[136:137], v[136:137], 1.0 op_sel_hi:[1,0]
	v_pk_add_f32 v[138:139], v[138:139], 1.0 op_sel_hi:[1,0]
	v_rcp_f32_e32 v136, v136
	v_rcp_f32_e32 v137, v137
	v_rcp_f32_e32 v138, v138
	v_rcp_f32_e32 v139, v139
	s_nop 0
	v_pk_mul_f32 v[124:125], v[124:125], v[136:137]
	v_pk_mul_f32 v[112:113], v[112:113], v[124:125]
	v_pk_mul_f32 v[124:125], v[126:127], v[138:139]
	v_pk_mul_f32 v[114:115], v[114:115], v[124:125]
	v_cvt_pk_bf16_f32 v200, v112, v113
	v_cvt_pk_bf16_f32 v201, v114, v115
.LBB0_892:
	s_or_b64 exec, exec, s[6:7]
	v_add_u32_e32 v136, 32, v190
	v_add_u32_e32 v137, s21, v136
	v_max_i32_e32 v138, 0, v137
	v_add_u32_e32 v112, s53, v191
	v_mul_hi_u32 v139, v138, s64
	v_add_u32_e32 v113, v112, v187
	ds_read_b128 v[124:127], v112 offset:512
	ds_read_b128 v[112:115], v113
	v_lshrrev_b32_e32 v139, 11, v139
	v_mul_i32_i24_e32 v140, 0xffffeff0, v139
	v_add_u32_e32 v138, v140, v138
	v_cmp_lt_i32_e32 vcc, 1, v136
	v_cmp_lt_i32_e64 s[8:9], 15, v138
	v_cmp_gt_i32_e64 s[6:7], s65, v137
	s_and_b64 s[8:9], vcc, s[8:9]
	s_waitcnt lgkmcnt(0)
	v_mov_b32_dpp v124, v108 row_shr:1 row_mask:0xf bank_mask:0xf
	v_mov_b32_dpp v112, v108 row_shr:2 row_mask:0xf bank_mask:0xf
	v_mov_b32_dpp v125, v109 row_shr:1 row_mask:0xf bank_mask:0xf
	v_mov_b32_dpp v113, v109 row_shr:2 row_mask:0xf bank_mask:0xf
	v_mov_b32_dpp v126, v110 row_shr:1 row_mask:0xf bank_mask:0xf
	v_mov_b32_dpp v114, v110 row_shr:2 row_mask:0xf bank_mask:0xf
	v_mov_b32_dpp v127, v111 row_shr:1 row_mask:0xf bank_mask:0xf
	v_mov_b32_dpp v115, v111 row_shr:2 row_mask:0xf bank_mask:0xf
	s_and_b64 s[30:31], s[8:9], s[6:7]
	v_lshl_add_u32 v136, v139, 12, v138
	s_and_saveexec_b64 s[6:7], s[30:31]
	s_cbranch_execz .LBB0_894
	v_pk_fma_f32 v[108:109], v[108:109], v[128:129], v[132:133]
	v_pk_fma_f32 v[110:111], v[110:111], v[130:131], v[134:135]
	v_pk_fma_f32 v[108:109], v[120:121], v[124:125], v[108:109]
	v_pk_fma_f32 v[110:111], v[122:123], v[126:127], v[110:111]
	v_pk_fma_f32 v[108:109], v[116:117], v[112:113], v[108:109]
	v_pk_fma_f32 v[110:111], v[118:119], v[114:115], v[110:111]
	v_pk_mul_f32 v[112:113], v[108:109], s[98:99] op_sel_hi:[1,0]
	v_pk_mul_f32 v[114:115], v[110:111], s[98:99] op_sel_hi:[1,0]
	v_pk_mul_f32 v[112:113], v[108:109], v[112:113]
	v_pk_mul_f32 v[114:115], v[110:111], v[114:115]
	v_pk_fma_f32 v[112:113], v[108:109], v[112:113], v[108:109]
	v_pk_fma_f32 v[114:115], v[110:111], v[114:115], v[110:111]
	v_pk_mul_f32 v[112:113], v[112:113], s[100:101] op_sel_hi:[1,0]
	v_pk_mul_f32 v[114:115], v[114:115], s[100:101] op_sel_hi:[1,0]
	v_exp_f32_e32 v112, v112
	v_exp_f32_e32 v113, v113
	v_exp_f32_e32 v114, v114
	v_exp_f32_e32 v115, v115
	v_pk_add_f32 v[112:113], v[112:113], 1.0 op_sel_hi:[1,0]
	v_pk_add_f32 v[114:115], v[114:115], 1.0 op_sel_hi:[1,0]
	v_rcp_f32_e32 v112, v112
	v_rcp_f32_e32 v113, v113
	v_rcp_f32_e32 v114, v114
	v_rcp_f32_e32 v115, v115
	s_nop 0
	v_pk_mul_f32 v[108:109], v[108:109], v[112:113]
	v_pk_mul_f32 v[104:105], v[104:105], v[108:109]
	v_pk_mul_f32 v[108:109], v[110:111], v[114:115]
	v_pk_mul_f32 v[106:107], v[106:107], v[108:109]
	v_cvt_pk_bf16_f32 v204, v104, v105
	v_cvt_pk_bf16_f32 v205, v106, v107
; #define LAS __attribute__((address_space(3)))
; __device__ __forceinline__ unsigned pk2e(float lo, float hi) { typedef __bf16 b2 __attribute__((ext_vector_type(2))); b2 v; v.x = (__bf16)lo; v.y = (__bf16)hi; return __builtin_bit_cast(unsigned, v); }
; __device__ __forceinline__ float ex2(float x) { return __builtin_amdgcn_exp2f(x); }
;     __device__ __forceinline__ void operator()(const f32x4 (&acc)[2][2][4][2], const Unit& u, int wr, int wc, int fr, int fq, LAS unsigned char* hb) const {
;     ...
;                 for (int m = 0; m < 4; ++m) { const int q = 8 * ai + 4 * wr + m, prev = q > 0 ? q - 1 : 0; const int lr = ai * HALF + wr * 64 + m * 16 + fr, R = R0 + lr;
;                     const int Rc = R < 0 ? 0 : R; const int b = Rc / LL, p = Rc - b * LL;
;                     const LAS unsigned char* hp = hb + (prev * H * NCH + chl + 4 * n) * 4;
;                     const f32x4 h1 = *(const LAS f32x4*)(hp + hr1 * NCH * 4), h2 = *(const LAS f32x4*)(hp + hr2 * NCH * 4);
;                     const f32x4 gv = acc[ai][0][m][n], uv = acc[ai][1][m][n];
;                     float o[4];
; #pragma unroll
;                     for (int j = 0; j < 4; ++j) { const float g = gv[j];
;                         float g1 = dpp_row_shr<1>(h1[j], g), g2 = dpp_row_shr<2>(h2[j], g);
;                         g1 = p >= 1 ? g1 : 0.f; g2 = p >= 2 ? g2 : 0.f;
;                         const float v = bs[j] + w2[j] * g + w1[j] * g1 + w0[j] * g2;
;                         const float a = v + 0.044715f * v * v * v;
;                         const float ge = v * __builtin_amdgcn_rcpf(1.f + ex2(-2.f * 0.7978845608028654f * 1.4426950408889634f * a));
;                         o[j] = ge * uv[j]; }
;                     if (lr >= H && R < TT && p >= NMETA) { u32x2 w; w.x = pk2e(o[0], o[1]); w.y = pk2e(o[2], o[3]);
;                         *(u32x2*)(ACT + ((size_t)b * SEQ + p - NMETA) * DFF + c4) = w; } }
.LBB0_894:
	s_or_b64 exec, exec, s[6:7]
	v_add_u32_e32 v112, 48, v190
	v_add_u32_e32 v113, s21, v112
	v_max_i32_e32 v114, 0, v113
	v_add_u32_e32 v104, s54, v191
	v_mul_hi_u32 v115, v114, s64
	v_add_u32_e32 v105, v104, v187
	ds_read_b128 v[108:111], v104 offset:512
	ds_read_b128 v[104:107], v105
	v_lshrrev_b32_e32 v115, 11, v115
	v_mul_i32_i24_e32 v124, 0xffffeff0, v115
	v_add_u32_e32 v114, v124, v114
	v_cmp_lt_i32_e32 vcc, 1, v112
	v_cmp_lt_i32_e64 s[8:9], 15, v114
	v_cmp_gt_i32_e64 s[6:7], s65, v113
	s_and_b64 s[8:9], vcc, s[8:9]
	s_waitcnt lgkmcnt(0)
	v_mov_b32_dpp v108, v100 row_shr:1 row_mask:0xf bank_mask:0xf
	v_mov_b32_dpp v104, v100 row_shr:2 row_mask:0xf bank_mask:0xf
	v_mov_b32_dpp v109, v101 row_shr:1 row_mask:0xf bank_mask:0xf
	v_mov_b32_dpp v105, v101 row_shr:2 row_mask:0xf bank_mask:0xf
	v_mov_b32_dpp v110, v102 row_shr:1 row_mask:0xf bank_mask:0xf
	v_mov_b32_dpp v106, v102 row_shr:2 row_mask:0xf bank_mask:0xf
	v_mov_b32_dpp v111, v103 row_shr:1 row_mask:0xf bank_mask:0xf
	v_mov_b32_dpp v107, v103 row_shr:2 row_mask:0xf bank_mask:0xf
	s_and_b64 s[34:35], s[8:9], s[6:7]
	v_lshl_add_u32 v112, v115, 12, v114
	s_and_saveexec_b64 s[6:7], s[34:35]
	s_cbranch_execz .LBB0_896
	v_pk_fma_f32 v[100:101], v[100:101], v[128:129], v[132:133]
	v_pk_fma_f32 v[102:103], v[102:103], v[130:131], v[134:135]
	v_pk_fma_f32 v[100:101], v[120:121], v[108:109], v[100:101]
	v_pk_fma_f32 v[102:103], v[122:123], v[110:111], v[102:103]
	v_pk_fma_f32 v[100:101], v[116:117], v[104:105], v[100:101]
	v_pk_fma_f32 v[102:103], v[118:119], v[106:107], v[102:103]
	v_pk_mul_f32 v[104:105], v[100:101], s[98:99] op_sel_hi:[1,0]
	v_pk_mul_f32 v[106:107], v[102:103], s[98:99] op_sel_hi:[1,0]
	v_pk_mul_f32 v[104:105], v[100:101], v[104:105]
	v_pk_mul_f32 v[106:107], v[102:103], v[106:107]
	v_pk_fma_f32 v[104:105], v[100:101], v[104:105], v[100:101]
	v_pk_fma_f32 v[106:107], v[102:103], v[106:107], v[102:103]
	v_pk_mul_f32 v[104:105], v[104:105], s[100:101] op_sel_hi:[1,0]
	v_pk_mul_f32 v[106:107], v[106:107], s[100:101] op_sel_hi:[1,0]
	v_exp_f32_e32 v104, v104
	v_exp_f32_e32 v105, v105
	v_exp_f32_e32 v106, v106
	v_exp_f32_e32 v107, v107
	v_pk_add_f32 v[104:105], v[104:105], 1.0 op_sel_hi:[1,0]
	v_pk_add_f32 v[106:107], v[106:107], 1.0 op_sel_hi:[1,0]
	v_rcp_f32_e32 v104, v104
	v_rcp_f32_e32 v105, v105
	v_rcp_f32_e32 v106, v106
	v_rcp_f32_e32 v107, v107
	s_nop 0
	v_pk_mul_f32 v[100:101], v[100:101], v[104:105]
	v_pk_mul_f32 v[96:97], v[96:97], v[100:101]
	v_pk_mul_f32 v[100:101], v[102:103], v[106:107]
	v_pk_mul_f32 v[98:99], v[98:99], v[100:101]
	v_cvt_pk_bf16_f32 v208, v96, v97
	v_cvt_pk_bf16_f32 v209, v98, v99
.LBB0_896:
	s_or_b64 exec, exec, s[6:7]
	v_add_u32_e32 v104, 0x80, v190
	v_add_u32_e32 v107, s21, v104
	v_max_i32_e32 v108, 0, v107
	v_mul_hi_u32 v109, v108, s64
	v_add_u32_e32 v105, s55, v188
	v_add_u32_e32 v106, v105, v187
	ds_read_b128 v[100:103], v105 offset:7680
	ds_read_b128 v[96:99], v106 offset:7168
	v_lshrrev_b32_e32 v109, 11, v109
	v_mul_i32_i24_e32 v110, 0xffffeff0, v109
	v_add_u32_e32 v108, v110, v108
	v_cmp_lt_i32_e32 vcc, 1, v104
	v_cmp_lt_i32_e64 s[8:9], 15, v108
	v_cmp_gt_i32_e64 s[6:7], s65, v107
	s_and_b64 s[8:9], vcc, s[8:9]
	s_waitcnt lgkmcnt(0)
	v_mov_b32_dpp v100, v92 row_shr:1 row_mask:0xf bank_mask:0xf
	v_mov_b32_dpp v96, v92 row_shr:2 row_mask:0xf bank_mask:0xf
	v_mov_b32_dpp v101, v93 row_shr:1 row_mask:0xf bank_mask:0xf
	v_mov_b32_dpp v97, v93 row_shr:2 row_mask:0xf bank_mask:0xf
	v_mov_b32_dpp v102, v94 row_shr:1 row_mask:0xf bank_mask:0xf
	v_mov_b32_dpp v98, v94 row_shr:2 row_mask:0xf bank_mask:0xf
	v_mov_b32_dpp v103, v95 row_shr:1 row_mask:0xf bank_mask:0xf
	v_mov_b32_dpp v99, v95 row_shr:2 row_mask:0xf bank_mask:0xf
	s_and_b64 s[36:37], s[8:9], s[6:7]
	v_lshl_add_u32 v104, v109, 12, v108
	s_and_saveexec_b64 s[6:7], s[36:37]
	s_cbranch_execz .LBB0_898
	v_pk_fma_f32 v[92:93], v[92:93], v[128:129], v[132:133]
	v_pk_fma_f32 v[94:95], v[94:95], v[130:131], v[134:135]
	v_pk_fma_f32 v[92:93], v[120:121], v[100:101], v[92:93]
	v_pk_fma_f32 v[94:95], v[122:123], v[102:103], v[94:95]
	v_pk_fma_f32 v[92:93], v[116:117], v[96:97], v[92:93]
	v_pk_fma_f32 v[94:95], v[118:119], v[98:99], v[94:95]
	v_pk_mul_f32 v[96:97], v[92:93], s[98:99] op_sel_hi:[1,0]
	v_pk_mul_f32 v[98:99], v[94:95], s[98:99] op_sel_hi:[1,0]
	v_pk_mul_f32 v[96:97], v[92:93], v[96:97]
	v_pk_mul_f32 v[98:99], v[94:95], v[98:99]
	v_pk_fma_f32 v[96:97], v[92:93], v[96:97], v[92:93]
	v_pk_fma_f32 v[98:99], v[94:95], v[98:99], v[94:95]
	v_pk_mul_f32 v[96:97], v[96:97], s[100:101] op_sel_hi:[1,0]
	v_pk_mul_f32 v[98:99], v[98:99], s[100:101] op_sel_hi:[1,0]
	v_exp_f32_e32 v96, v96
	v_exp_f32_e32 v97, v97
	v_exp_f32_e32 v98, v98
	v_exp_f32_e32 v99, v99
	v_pk_add_f32 v[96:97], v[96:97], 1.0 op_sel_hi:[1,0]
	v_pk_add_f32 v[98:99], v[98:99], 1.0 op_sel_hi:[1,0]
	v_rcp_f32_e32 v96, v96
	v_rcp_f32_e32 v97, v97
	v_rcp_f32_e32 v98, v98
	v_rcp_f32_e32 v99, v99
	s_nop 0
	v_pk_mul_f32 v[92:93], v[92:93], v[96:97]
	v_pk_mul_f32 v[88:89], v[88:89], v[92:93]
	v_pk_mul_f32 v[92:93], v[94:95], v[98:99]
	v_pk_mul_f32 v[90:91], v[90:91], v[92:93]
	v_cvt_pk_bf16_f32 v212, v88, v89
	v_cvt_pk_bf16_f32 v213, v90, v91
; #define LAS __attribute__((address_space(3)))
; __device__ __forceinline__ unsigned pk2e(float lo, float hi) { typedef __bf16 b2 __attribute__((ext_vector_type(2))); b2 v; v.x = (__bf16)lo; v.y = (__bf16)hi; return __builtin_bit_cast(unsigned, v); }
; __device__ __forceinline__ float ex2(float x) { return __builtin_amdgcn_exp2f(x); }
;     __device__ __forceinline__ void operator()(const f32x4 (&acc)[2][2][4][2], const Unit& u, int wr, int wc, int fr, int fq, LAS unsigned char* hb) const {
;     ...
;                 for (int m = 0; m < 4; ++m) { const int q = 8 * ai + 4 * wr + m, prev = q > 0 ? q - 1 : 0; const int lr = ai * HALF + wr * 64 + m * 16 + fr, R = R0 + lr;
;                     const int Rc = R < 0 ? 0 : R; const int b = Rc / LL, p = Rc - b * LL;
;                     const LAS unsigned char* hp = hb + (prev * H * NCH + chl + 4 * n) * 4;
;                     const f32x4 h1 = *(const LAS f32x4*)(hp + hr1 * NCH * 4), h2 = *(const LAS f32x4*)(hp + hr2 * NCH * 4);
;                     const f32x4 gv = acc[ai][0][m][n], uv = acc[ai][1][m][n];
;                     float o[4];
; #pragma unroll
;                     for (int j = 0; j < 4; ++j) { const float g = gv[j];
;                         float g1 = dpp_row_shr<1>(h1[j], g), g2 = dpp_row_shr<2>(h2[j], g);
;                         g1 = p >= 1 ? g1 : 0.f; g2 = p >= 2 ? g2 : 0.f;
;                         const float v = bs[j] + w2[j] * g + w1[j] * g1 + w0[j] * g2;
;                         const float a = v + 0.044715f * v * v * v;
;                         const float ge = v * __builtin_amdgcn_rcpf(1.f + ex2(-2.f * 0.7978845608028654f * 1.4426950408889634f * a));
;                         o[j] = ge * uv[j]; }
;                     if (lr >= H && R < TT && p >= NMETA) { u32x2 w; w.x = pk2e(o[0], o[1]); w.y = pk2e(o[2], o[3]);
;                         *(u32x2*)(ACT + ((size_t)b * SEQ + p - NMETA) * DFF + c4) = w; } }
.LBB0_898:
	s_or_b64 exec, exec, s[6:7]
	v_add_u32_e32 v96, 0x90, v190
	v_add_u32_e32 v99, s21, v96
	v_max_i32_e32 v100, 0, v99
	v_mul_hi_u32 v101, v100, s64
	v_add_u32_e32 v97, s56, v188
	v_add_u32_e32 v98, v97, v187
	ds_read_b128 v[92:95], v97 offset:8704
	ds_read_b128 v[88:91], v98 offset:8192
	v_lshrrev_b32_e32 v101, 11, v101
	v_mul_i32_i24_e32 v102, 0xffffeff0, v101
	v_add_u32_e32 v100, v102, v100
	v_cmp_lt_i32_e32 vcc, 1, v96
	v_cmp_lt_i32_e64 s[8:9], 15, v100
	v_cmp_gt_i32_e64 s[6:7], s65, v99
	s_and_b64 s[8:9], vcc, s[8:9]
	s_waitcnt lgkmcnt(0)
	v_mov_b32_dpp v92, v84 row_shr:1 row_mask:0xf bank_mask:0xf
	v_mov_b32_dpp v88, v84 row_shr:2 row_mask:0xf bank_mask:0xf
	v_mov_b32_dpp v93, v85 row_shr:1 row_mask:0xf bank_mask:0xf
	v_mov_b32_dpp v89, v85 row_shr:2 row_mask:0xf bank_mask:0xf
	v_mov_b32_dpp v94, v86 row_shr:1 row_mask:0xf bank_mask:0xf
	v_mov_b32_dpp v90, v86 row_shr:2 row_mask:0xf bank_mask:0xf
	v_mov_b32_dpp v95, v87 row_shr:1 row_mask:0xf bank_mask:0xf
	v_mov_b32_dpp v91, v87 row_shr:2 row_mask:0xf bank_mask:0xf
	s_and_b64 s[38:39], s[8:9], s[6:7]
	v_lshl_add_u32 v96, v101, 12, v100
	s_and_saveexec_b64 s[6:7], s[38:39]
	s_cbranch_execz .LBB0_900
	v_pk_fma_f32 v[84:85], v[84:85], v[128:129], v[132:133]
	v_pk_fma_f32 v[86:87], v[86:87], v[130:131], v[134:135]
	v_pk_fma_f32 v[84:85], v[120:121], v[92:93], v[84:85]
	v_pk_fma_f32 v[86:87], v[122:123], v[94:95], v[86:87]
	v_pk_fma_f32 v[84:85], v[116:117], v[88:89], v[84:85]
	v_pk_fma_f32 v[86:87], v[118:119], v[90:91], v[86:87]
	v_pk_mul_f32 v[88:89], v[84:85], s[98:99] op_sel_hi:[1,0]
	v_pk_mul_f32 v[90:91], v[86:87], s[98:99] op_sel_hi:[1,0]
	v_pk_mul_f32 v[88:89], v[84:85], v[88:89]
	v_pk_mul_f32 v[90:91], v[86:87], v[90:91]
	v_pk_fma_f32 v[88:89], v[84:85], v[88:89], v[84:85]
	v_pk_fma_f32 v[90:91], v[86:87], v[90:91], v[86:87]
	v_pk_mul_f32 v[88:89], v[88:89], s[100:101] op_sel_hi:[1,0]
	v_pk_mul_f32 v[90:91], v[90:91], s[100:101] op_sel_hi:[1,0]
	v_exp_f32_e32 v88, v88
	v_exp_f32_e32 v89, v89
	v_exp_f32_e32 v90, v90
	v_exp_f32_e32 v91, v91
	v_pk_add_f32 v[88:89], v[88:89], 1.0 op_sel_hi:[1,0]
	v_pk_add_f32 v[90:91], v[90:91], 1.0 op_sel_hi:[1,0]
	v_rcp_f32_e32 v88, v88
	v_rcp_f32_e32 v89, v89
	v_rcp_f32_e32 v90, v90
	v_rcp_f32_e32 v91, v91
	s_nop 0
	v_pk_mul_f32 v[84:85], v[84:85], v[88:89]
	v_pk_mul_f32 v[80:81], v[80:81], v[84:85]
	v_pk_mul_f32 v[84:85], v[86:87], v[90:91]
	v_pk_mul_f32 v[82:83], v[82:83], v[84:85]
	v_cvt_pk_bf16_f32 v216, v80, v81
	v_cvt_pk_bf16_f32 v217, v82, v83
.LBB0_900:
	s_or_b64 exec, exec, s[6:7]
	v_add_u32_e32 v88, 0xa0, v190
	v_add_u32_e32 v89, s21, v88
	v_max_i32_e32 v90, 0, v89
	v_mul_hi_u32 v91, v90, s64
	v_add_u32_e32 v92, s57, v188
	v_add_u32_e32 v93, v92, v187
	ds_read_b128 v[84:87], v92 offset:9728
	ds_read_b128 v[80:83], v93 offset:9216
	v_lshrrev_b32_e32 v91, 11, v91
	v_mul_i32_i24_e32 v94, 0xffffeff0, v91
	v_add_u32_e32 v90, v94, v90
	v_cmp_lt_i32_e32 vcc, 1, v88
	v_cmp_lt_i32_e64 s[8:9], 15, v90
	v_cmp_gt_i32_e64 s[6:7], s65, v89
	s_and_b64 s[8:9], vcc, s[8:9]
	s_waitcnt lgkmcnt(0)
	v_mov_b32_dpp v84, v76 row_shr:1 row_mask:0xf bank_mask:0xf
	v_mov_b32_dpp v80, v76 row_shr:2 row_mask:0xf bank_mask:0xf
	v_mov_b32_dpp v85, v77 row_shr:1 row_mask:0xf bank_mask:0xf
	v_mov_b32_dpp v81, v77 row_shr:2 row_mask:0xf bank_mask:0xf
	v_mov_b32_dpp v86, v78 row_shr:1 row_mask:0xf bank_mask:0xf
	v_mov_b32_dpp v82, v78 row_shr:2 row_mask:0xf bank_mask:0xf
	v_mov_b32_dpp v87, v79 row_shr:1 row_mask:0xf bank_mask:0xf
	v_mov_b32_dpp v83, v79 row_shr:2 row_mask:0xf bank_mask:0xf
	s_and_b64 s[40:41], s[8:9], s[6:7]
	v_lshl_add_u32 v90, v91, 12, v90
	s_and_saveexec_b64 s[6:7], s[40:41]
	s_cbranch_execz .LBB0_902
	v_pk_fma_f32 v[76:77], v[76:77], v[128:129], v[132:133]
	v_pk_fma_f32 v[78:79], v[78:79], v[130:131], v[134:135]
	v_pk_fma_f32 v[76:77], v[120:121], v[84:85], v[76:77]
	v_pk_fma_f32 v[78:79], v[122:123], v[86:87], v[78:79]
	v_pk_fma_f32 v[76:77], v[116:117], v[80:81], v[76:77]
	v_pk_fma_f32 v[78:79], v[118:119], v[82:83], v[78:79]
	v_pk_mul_f32 v[80:81], v[76:77], s[98:99] op_sel_hi:[1,0]
	v_pk_mul_f32 v[82:83], v[78:79], s[98:99] op_sel_hi:[1,0]
	v_pk_mul_f32 v[80:81], v[76:77], v[80:81]
	v_pk_mul_f32 v[82:83], v[78:79], v[82:83]
	v_pk_fma_f32 v[80:81], v[76:77], v[80:81], v[76:77]
	v_pk_fma_f32 v[82:83], v[78:79], v[82:83], v[78:79]
	v_pk_mul_f32 v[80:81], v[80:81], s[100:101] op_sel_hi:[1,0]
	v_pk_mul_f32 v[82:83], v[82:83], s[100:101] op_sel_hi:[1,0]
	v_exp_f32_e32 v80, v80
	v_exp_f32_e32 v81, v81
	v_exp_f32_e32 v82, v82
	v_exp_f32_e32 v83, v83
	v_pk_add_f32 v[80:81], v[80:81], 1.0 op_sel_hi:[1,0]
	v_pk_add_f32 v[82:83], v[82:83], 1.0 op_sel_hi:[1,0]
	v_rcp_f32_e32 v80, v80
	v_rcp_f32_e32 v81, v81
	v_rcp_f32_e32 v82, v82
	v_rcp_f32_e32 v83, v83
	s_nop 0
	v_pk_mul_f32 v[76:77], v[76:77], v[80:81]
	v_pk_mul_f32 v[72:73], v[72:73], v[76:77]
	v_pk_mul_f32 v[76:77], v[78:79], v[82:83]
	v_pk_mul_f32 v[74:75], v[74:75], v[76:77]
	v_cvt_pk_bf16_f32 v228, v72, v73
	v_cvt_pk_bf16_f32 v229, v74, v75
; #define LAS __attribute__((address_space(3)))
; __device__ __forceinline__ unsigned pk2e(float lo, float hi) { typedef __bf16 b2 __attribute__((ext_vector_type(2))); b2 v; v.x = (__bf16)lo; v.y = (__bf16)hi; return __builtin_bit_cast(unsigned, v); }
; __device__ __forceinline__ float ex2(float x) { return __builtin_amdgcn_exp2f(x); }
;     __device__ __forceinline__ void operator()(const f32x4 (&acc)[2][2][4][2], const Unit& u, int wr, int wc, int fr, int fq, LAS unsigned char* hb) const {
;     ...
;         for (int n = 0; n < 2; ++n) { asm volatile("" ::: "memory");
;             const int c4 = ch + 4 * n;
;             const f32x4 w0 = *(const f32x4*)(cw + 0 * DFF + c4), w1 = *(const f32x4*)(cw + 1 * DFF + c4), w2 = *(const f32x4*)(cw + 2 * DFF + c4), bs = *(const f32x4*)(cb + c4);
; #pragma unroll
;             for (int ai = 0; ai < 2; ++ai)
; #pragma unroll
;                 for (int m = 0; m < 4; ++m) { const int q = 8 * ai + 4 * wr + m, prev = q > 0 ? q - 1 : 0; const int lr = ai * HALF + wr * 64 + m * 16 + fr, R = R0 + lr;
;                     const int Rc = R < 0 ? 0 : R; const int b = Rc / LL, p = Rc - b * LL;
;                     const LAS unsigned char* hp = hb + (prev * H * NCH + chl + 4 * n) * 4;
;                     const f32x4 h1 = *(const LAS f32x4*)(hp + hr1 * NCH * 4), h2 = *(const LAS f32x4*)(hp + hr2 * NCH * 4);
;                     const f32x4 gv = acc[ai][0][m][n], uv = acc[ai][1][m][n];
;                     float o[4];
; #pragma unroll
;                     for (int j = 0; j < 4; ++j) { const float g = gv[j];
;                         float g1 = dpp_row_shr<1>(h1[j], g), g2 = dpp_row_shr<2>(h2[j], g);
;                         g1 = p >= 1 ? g1 : 0.f; g2 = p >= 2 ? g2 : 0.f;
;                         const float v = bs[j] + w2[j] * g + w1[j] * g1 + w0[j] * g2;
;                         const float a = v + 0.044715f * v * v * v;
;                         const float ge = v * __builtin_amdgcn_rcpf(1.f + ex2(-2.f * 0.7978845608028654f * 1.4426950408889634f * a));
;                         o[j] = ge * uv[j]; }
;                     if (lr >= H && R < TT && p >= NMETA) { u32x2 w; w.x = pk2e(o[0], o[1]); w.y = pk2e(o[2], o[3]);
;                         *(u32x2*)(ACT + ((size_t)b * SEQ + p - NMETA) * DFF + c4) = w; } }
.LBB0_902:
	s_or_b64 exec, exec, s[6:7]
	v_add_u32_e32 v80, 0xb0, v190
	v_add_u32_e32 v81, s21, v80
	v_max_i32_e32 v82, 0, v81
	v_mul_hi_u32 v83, v82, s64
	v_add_u32_e32 v94, s58, v188
	v_add_u32_e32 v95, v94, v187
	ds_read_b128 v[76:79], v94 offset:10752
	ds_read_b128 v[72:75], v95 offset:10240
	v_lshrrev_b32_e32 v83, 11, v83
	v_mul_i32_i24_e32 v84, 0xffffeff0, v83
	v_add_u32_e32 v82, v84, v82
	v_cmp_lt_i32_e32 vcc, 1, v80
	v_cmp_lt_i32_e64 s[8:9], 15, v82
	v_cmp_gt_i32_e64 s[6:7], s65, v81
	s_and_b64 s[8:9], vcc, s[8:9]
	s_waitcnt lgkmcnt(0)
	v_mov_b32_dpp v76, v68 row_shr:1 row_mask:0xf bank_mask:0xf
	v_mov_b32_dpp v72, v68 row_shr:2 row_mask:0xf bank_mask:0xf
	v_mov_b32_dpp v77, v69 row_shr:1 row_mask:0xf bank_mask:0xf
	v_mov_b32_dpp v73, v69 row_shr:2 row_mask:0xf bank_mask:0xf
	v_mov_b32_dpp v78, v70 row_shr:1 row_mask:0xf bank_mask:0xf
	v_mov_b32_dpp v74, v70 row_shr:2 row_mask:0xf bank_mask:0xf
	v_mov_b32_dpp v79, v71 row_shr:1 row_mask:0xf bank_mask:0xf
	v_mov_b32_dpp v75, v71 row_shr:2 row_mask:0xf bank_mask:0xf
	s_and_b64 s[6:7], s[8:9], s[6:7]
	v_lshl_add_u32 v91, v83, 12, v82
	s_and_saveexec_b64 s[8:9], s[6:7]
	s_cbranch_execz .LBB0_904
	v_pk_fma_f32 v[68:69], v[68:69], v[128:129], v[132:133]
	v_pk_fma_f32 v[70:71], v[70:71], v[130:131], v[134:135]
	v_pk_fma_f32 v[68:69], v[120:121], v[76:77], v[68:69]
	v_pk_fma_f32 v[70:71], v[122:123], v[78:79], v[70:71]
	v_pk_fma_f32 v[68:69], v[116:117], v[72:73], v[68:69]
	v_pk_fma_f32 v[70:71], v[118:119], v[74:75], v[70:71]
	v_pk_mul_f32 v[72:73], v[68:69], s[98:99] op_sel_hi:[1,0]
	v_pk_mul_f32 v[74:75], v[70:71], s[98:99] op_sel_hi:[1,0]
	v_pk_mul_f32 v[72:73], v[68:69], v[72:73]
	v_pk_mul_f32 v[74:75], v[70:71], v[74:75]
	v_pk_fma_f32 v[72:73], v[68:69], v[72:73], v[68:69]
	v_pk_fma_f32 v[74:75], v[70:71], v[74:75], v[70:71]
	v_pk_mul_f32 v[72:73], v[72:73], s[100:101] op_sel_hi:[1,0]
	v_pk_mul_f32 v[74:75], v[74:75], s[100:101] op_sel_hi:[1,0]
	v_exp_f32_e32 v72, v72
	v_exp_f32_e32 v73, v73
	v_exp_f32_e32 v74, v74
	v_exp_f32_e32 v75, v75
	v_pk_add_f32 v[72:73], v[72:73], 1.0 op_sel_hi:[1,0]
	v_pk_add_f32 v[74:75], v[74:75], 1.0 op_sel_hi:[1,0]
	v_rcp_f32_e32 v72, v72
	v_rcp_f32_e32 v73, v73
	v_rcp_f32_e32 v74, v74
	v_rcp_f32_e32 v75, v75
	s_nop 0
	v_pk_mul_f32 v[68:69], v[68:69], v[72:73]
	v_pk_mul_f32 v[60:61], v[60:61], v[68:69]
	v_pk_mul_f32 v[68:69], v[70:71], v[74:75]
	v_pk_mul_f32 v[62:63], v[62:63], v[68:69]
	v_cvt_pk_bf16_f32 v232, v60, v61
	v_cvt_pk_bf16_f32 v233, v62, v63
.LBB0_904:
	s_or_b64 exec, exec, s[8:9]
	global_load_dwordx4 v[60:63], v[172:173], off offset:16
	global_load_dwordx4 v[68:71], v[174:175], off offset:16
	global_load_dwordx4 v[72:75], v[176:177], off offset:16
	global_load_dwordx4 v[76:79], v[178:179], off offset:16
	v_add_u32_e32 v99, 0xfffffc10, v188
	v_add_u32_e32 v80, s51, v99
	v_add_u32_e32 v81, v80, v187
	ds_read_b128 v[84:87], v80 offset:512
	ds_read_b128 v[80:83], v81
	v_add_u32_e32 v88, 4, v170
	v_ashrrev_i32_e32 v89, 31, v88
	s_waitcnt lgkmcnt(0)
	v_mov_b32_dpp v84, v64 row_shr:1 row_mask:0xf bank_mask:0xf
	v_mov_b32_dpp v80, v64 row_shr:2 row_mask:0xf bank_mask:0xf
	v_mov_b32_dpp v85, v65 row_shr:1 row_mask:0xf bank_mask:0xf
	v_mov_b32_dpp v81, v65 row_shr:2 row_mask:0xf bank_mask:0xf
	v_mov_b32_dpp v86, v66 row_shr:1 row_mask:0xf bank_mask:0xf
	v_mov_b32_dpp v82, v66 row_shr:2 row_mask:0xf bank_mask:0xf
	v_mov_b32_dpp v87, v67 row_shr:1 row_mask:0xf bank_mask:0xf
	v_mov_b32_dpp v83, v67 row_shr:2 row_mask:0xf bank_mask:0xf
	s_waitcnt vmcnt(0)
	s_and_saveexec_b64 s[8:9], s[26:27]
	s_cbranch_execz .LBB0_906
	v_pk_fma_f32 v[64:65], v[64:65], v[72:73], v[76:77]
	v_pk_fma_f32 v[66:67], v[66:67], v[74:75], v[78:79]
	v_pk_fma_f32 v[64:65], v[68:69], v[84:85], v[64:65]
	v_pk_fma_f32 v[66:67], v[70:71], v[86:87], v[66:67]
	v_pk_fma_f32 v[64:65], v[60:61], v[80:81], v[64:65]
	v_pk_fma_f32 v[66:67], v[62:63], v[82:83], v[66:67]
	v_pk_mul_f32 v[80:81], v[64:65], s[98:99] op_sel_hi:[1,0]
	v_pk_mul_f32 v[82:83], v[66:67], s[98:99] op_sel_hi:[1,0]
	v_pk_mul_f32 v[80:81], v[64:65], v[80:81]
	v_pk_mul_f32 v[82:83], v[66:67], v[82:83]
	v_pk_fma_f32 v[80:81], v[64:65], v[80:81], v[64:65]
	v_pk_fma_f32 v[82:83], v[66:67], v[82:83], v[66:67]
	v_pk_mul_f32 v[80:81], v[80:81], s[100:101] op_sel_hi:[1,0]
	v_pk_mul_f32 v[82:83], v[82:83], s[100:101] op_sel_hi:[1,0]
	v_exp_f32_e32 v80, v80
	v_exp_f32_e32 v81, v81
	v_exp_f32_e32 v82, v82
	v_exp_f32_e32 v83, v83
	v_pk_add_f32 v[80:81], v[80:81], 1.0 op_sel_hi:[1,0]
	v_pk_add_f32 v[82:83], v[82:83], 1.0 op_sel_hi:[1,0]
	v_rcp_f32_e32 v80, v80
	v_rcp_f32_e32 v81, v81
	v_rcp_f32_e32 v82, v82
	v_rcp_f32_e32 v83, v83
	s_nop 0
	v_pk_mul_f32 v[64:65], v[64:65], v[80:81]
	v_readlane_b32 s12, v237, 50
	v_pk_mul_f32 v[56:57], v[56:57], v[64:65]
	v_pk_mul_f32 v[64:65], v[66:67], v[82:83]
	v_readlane_b32 s13, v237, 51
	v_pk_mul_f32 v[58:59], v[58:59], v[64:65]
	v_cvt_pk_bf16_f32 v198, v56, v57
	v_cvt_pk_bf16_f32 v199, v58, v59
	v_mov_b64_e32 v[58:59], s[12:13]
	v_mad_u64_u32 v[58:59], s[26:27], v189, s66, v[58:59]
	v_lshl_add_u64 v[58:59], v[88:89], 1, v[58:59]
	v_add_co_u32_e32 v58, vcc, 0xfffea000, v58
	s_nop 1
	v_addc_co_u32_e32 v59, vcc, -1, v59, vcc
	global_store_dwordx4 v[58:59], v[196:199], off offset:-8
; #define LAS __attribute__((address_space(3)))
; __device__ __forceinline__ unsigned pk2e(float lo, float hi) { typedef __bf16 b2 __attribute__((ext_vector_type(2))); b2 v; v.x = (__bf16)lo; v.y = (__bf16)hi; return __builtin_bit_cast(unsigned, v); }
; __device__ __forceinline__ float ex2(float x) { return __builtin_amdgcn_exp2f(x); }
;     __device__ __forceinline__ void operator()(const f32x4 (&acc)[2][2][4][2], const Unit& u, int wr, int wc, int fr, int fq, LAS unsigned char* hb) const {
;     ...
;                 for (int m = 0; m < 4; ++m) { const int q = 8 * ai + 4 * wr + m, prev = q > 0 ? q - 1 : 0; const int lr = ai * HALF + wr * 64 + m * 16 + fr, R = R0 + lr;
;                     const int Rc = R < 0 ? 0 : R; const int b = Rc / LL, p = Rc - b * LL;
;                     const LAS unsigned char* hp = hb + (prev * H * NCH + chl + 4 * n) * 4;
;                     const f32x4 h1 = *(const LAS f32x4*)(hp + hr1 * NCH * 4), h2 = *(const LAS f32x4*)(hp + hr2 * NCH * 4);
;                     const f32x4 gv = acc[ai][0][m][n], uv = acc[ai][1][m][n];
;                     float o[4];
; #pragma unroll
;                     for (int j = 0; j < 4; ++j) { const float g = gv[j];
;                         float g1 = dpp_row_shr<1>(h1[j], g), g2 = dpp_row_shr<2>(h2[j], g);
;                         g1 = p >= 1 ? g1 : 0.f; g2 = p >= 2 ? g2 : 0.f;
;                         const float v = bs[j] + w2[j] * g + w1[j] * g1 + w0[j] * g2;
;                         const float a = v + 0.044715f * v * v * v;
;                         const float ge = v * __builtin_amdgcn_rcpf(1.f + ex2(-2.f * 0.7978845608028654f * 1.4426950408889634f * a));
;                         o[j] = ge * uv[j]; }
;                     if (lr >= H && R < TT && p >= NMETA) { u32x2 w; w.x = pk2e(o[0], o[1]); w.y = pk2e(o[2], o[3]);
;                         *(u32x2*)(ACT + ((size_t)b * SEQ + p - NMETA) * DFF + c4) = w; } }
.LBB0_906:
	s_or_b64 exec, exec, s[8:9]
	v_add_u32_e32 v56, s52, v99
	ds_read_b128 v[64:67], v56 offset:512
	v_add_u32_e32 v56, v56, v187
	ds_read_b128 v[56:59], v56
	s_waitcnt lgkmcnt(0)
	v_mov_b32_dpp v64, v52 row_shr:1 row_mask:0xf bank_mask:0xf
	v_mov_b32_dpp v65, v53 row_shr:1 row_mask:0xf bank_mask:0xf
	v_mov_b32_dpp v56, v52 row_shr:2 row_mask:0xf bank_mask:0xf
	v_mov_b32_dpp v57, v53 row_shr:2 row_mask:0xf bank_mask:0xf
	v_mov_b32_dpp v66, v54 row_shr:1 row_mask:0xf bank_mask:0xf
	v_mov_b32_dpp v58, v54 row_shr:2 row_mask:0xf bank_mask:0xf
	v_mov_b32_dpp v67, v55 row_shr:1 row_mask:0xf bank_mask:0xf
	v_mov_b32_dpp v59, v55 row_shr:2 row_mask:0xf bank_mask:0xf
	s_and_saveexec_b64 s[8:9], s[28:29]
	s_cbranch_execz .LBB0_908
	v_pk_fma_f32 v[52:53], v[52:53], v[72:73], v[76:77]
	v_pk_fma_f32 v[54:55], v[54:55], v[74:75], v[78:79]
	v_pk_fma_f32 v[52:53], v[68:69], v[64:65], v[52:53]
	v_pk_fma_f32 v[54:55], v[70:71], v[66:67], v[54:55]
	v_pk_fma_f32 v[52:53], v[60:61], v[56:57], v[52:53]
	v_pk_fma_f32 v[54:55], v[62:63], v[58:59], v[54:55]
	v_pk_mul_f32 v[56:57], v[52:53], s[98:99] op_sel_hi:[1,0]
	v_pk_mul_f32 v[58:59], v[54:55], s[98:99] op_sel_hi:[1,0]
	v_pk_mul_f32 v[56:57], v[52:53], v[56:57]
	v_pk_mul_f32 v[58:59], v[54:55], v[58:59]
	v_pk_fma_f32 v[56:57], v[52:53], v[56:57], v[52:53]
	v_pk_fma_f32 v[58:59], v[54:55], v[58:59], v[54:55]
	v_pk_mul_f32 v[56:57], v[56:57], s[100:101] op_sel_hi:[1,0]
	v_pk_mul_f32 v[58:59], v[58:59], s[100:101] op_sel_hi:[1,0]
	v_exp_f32_e32 v56, v56
	v_exp_f32_e32 v57, v57
	v_exp_f32_e32 v58, v58
	v_exp_f32_e32 v59, v59
	v_pk_add_f32 v[56:57], v[56:57], 1.0 op_sel_hi:[1,0]
	v_pk_add_f32 v[58:59], v[58:59], 1.0 op_sel_hi:[1,0]
	v_rcp_f32_e32 v56, v56
	v_rcp_f32_e32 v57, v57
	v_rcp_f32_e32 v58, v58
	v_rcp_f32_e32 v59, v59
	s_nop 0
	v_pk_mul_f32 v[52:53], v[52:53], v[56:57]
	v_readlane_b32 s12, v237, 50
	v_pk_mul_f32 v[48:49], v[48:49], v[52:53]
	v_pk_mul_f32 v[52:53], v[54:55], v[58:59]
	v_readlane_b32 s13, v237, 51
	v_pk_mul_f32 v[50:51], v[50:51], v[52:53]
	v_cvt_pk_bf16_f32 v202, v48, v49
	v_cvt_pk_bf16_f32 v203, v50, v51
	v_mov_b64_e32 v[50:51], s[12:13]
	v_mad_u64_u32 v[50:51], s[26:27], v144, s66, v[50:51]
	v_lshl_add_u64 v[50:51], v[88:89], 1, v[50:51]
	v_add_co_u32_e32 v50, vcc, 0xfffea000, v50
	s_nop 1
	v_addc_co_u32_e32 v51, vcc, -1, v51, vcc
	global_store_dwordx4 v[50:51], v[200:203], off offset:-8
.LBB0_908:
	s_or_b64 exec, exec, s[8:9]
	v_add_u32_e32 v48, s53, v99
	ds_read_b128 v[52:55], v48 offset:512
	v_add_u32_e32 v48, v48, v187
	ds_read_b128 v[48:51], v48
	s_waitcnt lgkmcnt(0)
	v_mov_b32_dpp v52, v44 row_shr:1 row_mask:0xf bank_mask:0xf
	v_mov_b32_dpp v53, v45 row_shr:1 row_mask:0xf bank_mask:0xf
	v_mov_b32_dpp v48, v44 row_shr:2 row_mask:0xf bank_mask:0xf
	v_mov_b32_dpp v49, v45 row_shr:2 row_mask:0xf bank_mask:0xf
	v_mov_b32_dpp v54, v46 row_shr:1 row_mask:0xf bank_mask:0xf
	v_mov_b32_dpp v50, v46 row_shr:2 row_mask:0xf bank_mask:0xf
	v_mov_b32_dpp v55, v47 row_shr:1 row_mask:0xf bank_mask:0xf
	v_mov_b32_dpp v51, v47 row_shr:2 row_mask:0xf bank_mask:0xf
	s_and_saveexec_b64 s[8:9], s[30:31]
	s_cbranch_execz .LBB0_910
	v_pk_fma_f32 v[44:45], v[44:45], v[72:73], v[76:77]
	v_pk_fma_f32 v[46:47], v[46:47], v[74:75], v[78:79]
	v_pk_fma_f32 v[44:45], v[68:69], v[52:53], v[44:45]
	v_pk_fma_f32 v[46:47], v[70:71], v[54:55], v[46:47]
	v_pk_fma_f32 v[44:45], v[60:61], v[48:49], v[44:45]
	v_pk_fma_f32 v[46:47], v[62:63], v[50:51], v[46:47]
	v_pk_mul_f32 v[48:49], v[44:45], s[98:99] op_sel_hi:[1,0]
	v_pk_mul_f32 v[50:51], v[46:47], s[98:99] op_sel_hi:[1,0]
	v_pk_mul_f32 v[48:49], v[44:45], v[48:49]
	v_pk_mul_f32 v[50:51], v[46:47], v[50:51]
	v_pk_fma_f32 v[48:49], v[44:45], v[48:49], v[44:45]
	v_pk_fma_f32 v[50:51], v[46:47], v[50:51], v[46:47]
	v_pk_mul_f32 v[48:49], v[48:49], s[100:101] op_sel_hi:[1,0]
	v_pk_mul_f32 v[50:51], v[50:51], s[100:101] op_sel_hi:[1,0]
	v_exp_f32_e32 v48, v48
	v_exp_f32_e32 v49, v49
	v_exp_f32_e32 v50, v50
	v_exp_f32_e32 v51, v51
	v_pk_add_f32 v[48:49], v[48:49], 1.0 op_sel_hi:[1,0]
	v_pk_add_f32 v[50:51], v[50:51], 1.0 op_sel_hi:[1,0]
	v_rcp_f32_e32 v48, v48
	v_rcp_f32_e32 v49, v49
	v_rcp_f32_e32 v50, v50
	v_rcp_f32_e32 v51, v51
	s_nop 0
	v_pk_mul_f32 v[44:45], v[44:45], v[48:49]
	v_readlane_b32 s12, v237, 50
	v_pk_mul_f32 v[40:41], v[40:41], v[44:45]
	v_pk_mul_f32 v[44:45], v[46:47], v[50:51]
	v_readlane_b32 s13, v237, 51
	v_pk_mul_f32 v[42:43], v[42:43], v[44:45]
	v_cvt_pk_bf16_f32 v206, v40, v41
	v_cvt_pk_bf16_f32 v207, v42, v43
	v_mov_b64_e32 v[42:43], s[12:13]
	v_mad_u64_u32 v[42:43], s[26:27], v136, s66, v[42:43]
	v_lshl_add_u64 v[42:43], v[88:89], 1, v[42:43]
	v_add_co_u32_e32 v42, vcc, 0xfffea000, v42
	s_nop 1
	v_addc_co_u32_e32 v43, vcc, -1, v43, vcc
	global_store_dwordx4 v[42:43], v[204:207], off offset:-8
; #define LAS __attribute__((address_space(3)))
; __device__ __forceinline__ unsigned pk2e(float lo, float hi) { typedef __bf16 b2 __attribute__((ext_vector_type(2))); b2 v; v.x = (__bf16)lo; v.y = (__bf16)hi; return __builtin_bit_cast(unsigned, v); }
; __device__ __forceinline__ float ex2(float x) { return __builtin_amdgcn_exp2f(x); }
;     __device__ __forceinline__ void operator()(const f32x4 (&acc)[2][2][4][2], const Unit& u, int wr, int wc, int fr, int fq, LAS unsigned char* hb) const {
;     ...
;                 for (int m = 0; m < 4; ++m) { const int q = 8 * ai + 4 * wr + m, prev = q > 0 ? q - 1 : 0; const int lr = ai * HALF + wr * 64 + m * 16 + fr, R = R0 + lr;
;                     const int Rc = R < 0 ? 0 : R; const int b = Rc / LL, p = Rc - b * LL;
;                     const LAS unsigned char* hp = hb + (prev * H * NCH + chl + 4 * n) * 4;
;                     const f32x4 h1 = *(const LAS f32x4*)(hp + hr1 * NCH * 4), h2 = *(const LAS f32x4*)(hp + hr2 * NCH * 4);
;                     const f32x4 gv = acc[ai][0][m][n], uv = acc[ai][1][m][n];
;                     float o[4];
; #pragma unroll
;                     for (int j = 0; j < 4; ++j) { const float g = gv[j];
;                         float g1 = dpp_row_shr<1>(h1[j], g), g2 = dpp_row_shr<2>(h2[j], g);
;                         g1 = p >= 1 ? g1 : 0.f; g2 = p >= 2 ? g2 : 0.f;
;                         const float v = bs[j] + w2[j] * g + w1[j] * g1 + w0[j] * g2;
;                         const float a = v + 0.044715f * v * v * v;
;                         const float ge = v * __builtin_amdgcn_rcpf(1.f + ex2(-2.f * 0.7978845608028654f * 1.4426950408889634f * a));
;                         o[j] = ge * uv[j]; }
;                     if (lr >= H && R < TT && p >= NMETA) { u32x2 w; w.x = pk2e(o[0], o[1]); w.y = pk2e(o[2], o[3]);
;                         *(u32x2*)(ACT + ((size_t)b * SEQ + p - NMETA) * DFF + c4) = w; } }
.LBB0_910:
	s_or_b64 exec, exec, s[8:9]
	v_add_u32_e32 v40, s54, v99
	ds_read_b128 v[44:47], v40 offset:512
	v_add_u32_e32 v40, v40, v187
	ds_read_b128 v[40:43], v40
	s_waitcnt lgkmcnt(0)
	v_mov_b32_dpp v44, v36 row_shr:1 row_mask:0xf bank_mask:0xf
	v_mov_b32_dpp v45, v37 row_shr:1 row_mask:0xf bank_mask:0xf
	v_mov_b32_dpp v40, v36 row_shr:2 row_mask:0xf bank_mask:0xf
	v_mov_b32_dpp v41, v37 row_shr:2 row_mask:0xf bank_mask:0xf
	v_mov_b32_dpp v46, v38 row_shr:1 row_mask:0xf bank_mask:0xf
	v_mov_b32_dpp v42, v38 row_shr:2 row_mask:0xf bank_mask:0xf
	v_mov_b32_dpp v47, v39 row_shr:1 row_mask:0xf bank_mask:0xf
	v_mov_b32_dpp v43, v39 row_shr:2 row_mask:0xf bank_mask:0xf
	s_and_saveexec_b64 s[8:9], s[34:35]
	s_cbranch_execz .LBB0_912
	v_pk_fma_f32 v[36:37], v[36:37], v[72:73], v[76:77]
	v_pk_fma_f32 v[38:39], v[38:39], v[74:75], v[78:79]
	v_pk_fma_f32 v[36:37], v[68:69], v[44:45], v[36:37]
	v_pk_fma_f32 v[38:39], v[70:71], v[46:47], v[38:39]
	v_pk_fma_f32 v[36:37], v[60:61], v[40:41], v[36:37]
	v_pk_fma_f32 v[38:39], v[62:63], v[42:43], v[38:39]
	v_pk_mul_f32 v[40:41], v[36:37], s[98:99] op_sel_hi:[1,0]
	v_pk_mul_f32 v[42:43], v[38:39], s[98:99] op_sel_hi:[1,0]
	v_pk_mul_f32 v[40:41], v[36:37], v[40:41]
	v_pk_mul_f32 v[42:43], v[38:39], v[42:43]
	v_pk_fma_f32 v[40:41], v[36:37], v[40:41], v[36:37]
	v_pk_fma_f32 v[42:43], v[38:39], v[42:43], v[38:39]
	v_pk_mul_f32 v[40:41], v[40:41], s[100:101] op_sel_hi:[1,0]
	v_pk_mul_f32 v[42:43], v[42:43], s[100:101] op_sel_hi:[1,0]
	v_exp_f32_e32 v40, v40
	v_exp_f32_e32 v41, v41
	v_exp_f32_e32 v42, v42
	v_exp_f32_e32 v43, v43
	v_pk_add_f32 v[40:41], v[40:41], 1.0 op_sel_hi:[1,0]
	v_pk_add_f32 v[42:43], v[42:43], 1.0 op_sel_hi:[1,0]
	v_rcp_f32_e32 v40, v40
	v_rcp_f32_e32 v41, v41
	v_rcp_f32_e32 v42, v42
	v_rcp_f32_e32 v43, v43
	s_nop 0
	v_pk_mul_f32 v[36:37], v[36:37], v[40:41]
	v_readlane_b32 s12, v237, 50
	v_pk_mul_f32 v[32:33], v[32:33], v[36:37]
	v_pk_mul_f32 v[36:37], v[38:39], v[42:43]
	v_readlane_b32 s13, v237, 51
	v_pk_mul_f32 v[34:35], v[34:35], v[36:37]
	v_cvt_pk_bf16_f32 v210, v32, v33
	v_cvt_pk_bf16_f32 v211, v34, v35
	v_mov_b64_e32 v[34:35], s[12:13]
	v_mad_u64_u32 v[34:35], s[26:27], v112, s66, v[34:35]
	v_lshl_add_u64 v[34:35], v[88:89], 1, v[34:35]
	v_add_co_u32_e32 v34, vcc, 0xfffea000, v34
	s_nop 1
	v_addc_co_u32_e32 v35, vcc, -1, v35, vcc
	global_store_dwordx4 v[34:35], v[208:211], off offset:-8
.LBB0_912:
	s_or_b64 exec, exec, s[8:9]
	ds_read_b128 v[36:39], v105 offset:7696
	ds_read_b128 v[32:35], v106 offset:7184
	s_waitcnt lgkmcnt(0)
	v_mov_b32_dpp v36, v28 row_shr:1 row_mask:0xf bank_mask:0xf
	v_mov_b32_dpp v32, v28 row_shr:2 row_mask:0xf bank_mask:0xf
	v_mov_b32_dpp v37, v29 row_shr:1 row_mask:0xf bank_mask:0xf
	v_mov_b32_dpp v33, v29 row_shr:2 row_mask:0xf bank_mask:0xf
	v_mov_b32_dpp v38, v30 row_shr:1 row_mask:0xf bank_mask:0xf
	v_mov_b32_dpp v34, v30 row_shr:2 row_mask:0xf bank_mask:0xf
	v_mov_b32_dpp v39, v31 row_shr:1 row_mask:0xf bank_mask:0xf
	v_mov_b32_dpp v35, v31 row_shr:2 row_mask:0xf bank_mask:0xf
	s_and_saveexec_b64 s[8:9], s[36:37]
	s_cbranch_execz .LBB0_914
	v_pk_fma_f32 v[28:29], v[28:29], v[72:73], v[76:77]
	v_pk_fma_f32 v[30:31], v[30:31], v[74:75], v[78:79]
	v_pk_fma_f32 v[28:29], v[68:69], v[36:37], v[28:29]
	v_pk_fma_f32 v[30:31], v[70:71], v[38:39], v[30:31]
	v_pk_fma_f32 v[28:29], v[60:61], v[32:33], v[28:29]
	v_pk_fma_f32 v[30:31], v[62:63], v[34:35], v[30:31]
	v_pk_mul_f32 v[32:33], v[28:29], s[98:99] op_sel_hi:[1,0]
	v_pk_mul_f32 v[34:35], v[30:31], s[98:99] op_sel_hi:[1,0]
	v_pk_mul_f32 v[32:33], v[28:29], v[32:33]
	v_pk_mul_f32 v[34:35], v[30:31], v[34:35]
	v_pk_fma_f32 v[32:33], v[28:29], v[32:33], v[28:29]
	v_pk_fma_f32 v[34:35], v[30:31], v[34:35], v[30:31]
	v_pk_mul_f32 v[32:33], v[32:33], s[100:101] op_sel_hi:[1,0]
	v_pk_mul_f32 v[34:35], v[34:35], s[100:101] op_sel_hi:[1,0]
	v_exp_f32_e32 v32, v32
	v_exp_f32_e32 v33, v33
	v_exp_f32_e32 v34, v34
	v_exp_f32_e32 v35, v35
	v_pk_add_f32 v[32:33], v[32:33], 1.0 op_sel_hi:[1,0]
	v_pk_add_f32 v[34:35], v[34:35], 1.0 op_sel_hi:[1,0]
	v_rcp_f32_e32 v32, v32
	v_rcp_f32_e32 v33, v33
	v_rcp_f32_e32 v34, v34
	v_rcp_f32_e32 v35, v35
	s_nop 0
	v_pk_mul_f32 v[28:29], v[28:29], v[32:33]
	v_readlane_b32 s12, v237, 50
	v_pk_mul_f32 v[24:25], v[24:25], v[28:29]
	v_pk_mul_f32 v[28:29], v[30:31], v[34:35]
	v_readlane_b32 s13, v237, 51
	v_pk_mul_f32 v[26:27], v[26:27], v[28:29]
	v_cvt_pk_bf16_f32 v214, v24, v25
	v_cvt_pk_bf16_f32 v215, v26, v27
	v_mov_b64_e32 v[26:27], s[12:13]
	v_mad_u64_u32 v[26:27], s[26:27], v104, s66, v[26:27]
	v_lshl_add_u64 v[26:27], v[88:89], 1, v[26:27]
	v_add_co_u32_e32 v26, vcc, 0xfffea000, v26
	s_nop 1
	v_addc_co_u32_e32 v27, vcc, -1, v27, vcc
	global_store_dwordx4 v[26:27], v[212:215], off offset:-8
; #define LAS __attribute__((address_space(3)))
; __device__ __forceinline__ unsigned pk2e(float lo, float hi) { typedef __bf16 b2 __attribute__((ext_vector_type(2))); b2 v; v.x = (__bf16)lo; v.y = (__bf16)hi; return __builtin_bit_cast(unsigned, v); }
; __device__ __forceinline__ float ex2(float x) { return __builtin_amdgcn_exp2f(x); }
;     __device__ __forceinline__ void operator()(const f32x4 (&acc)[2][2][4][2], const Unit& u, int wr, int wc, int fr, int fq, LAS unsigned char* hb) const {
;     ...
;                 for (int m = 0; m < 4; ++m) { const int q = 8 * ai + 4 * wr + m, prev = q > 0 ? q - 1 : 0; const int lr = ai * HALF + wr * 64 + m * 16 + fr, R = R0 + lr;
;                     const int Rc = R < 0 ? 0 : R; const int b = Rc / LL, p = Rc - b * LL;
;                     const LAS unsigned char* hp = hb + (prev * H * NCH + chl + 4 * n) * 4;
;                     const f32x4 h1 = *(const LAS f32x4*)(hp + hr1 * NCH * 4), h2 = *(const LAS f32x4*)(hp + hr2 * NCH * 4);
;                     const f32x4 gv = acc[ai][0][m][n], uv = acc[ai][1][m][n];
;                     float o[4];
; #pragma unroll
;                     for (int j = 0; j < 4; ++j) { const float g = gv[j];
;                         float g1 = dpp_row_shr<1>(h1[j], g), g2 = dpp_row_shr<2>(h2[j], g);
;                         g1 = p >= 1 ? g1 : 0.f; g2 = p >= 2 ? g2 : 0.f;
;                         const float v = bs[j] + w2[j] * g + w1[j] * g1 + w0[j] * g2;
;                         const float a = v + 0.044715f * v * v * v;
;                         const float ge = v * __builtin_amdgcn_rcpf(1.f + ex2(-2.f * 0.7978845608028654f * 1.4426950408889634f * a));
;                         o[j] = ge * uv[j]; }
;                     if (lr >= H && R < TT && p >= NMETA) { u32x2 w; w.x = pk2e(o[0], o[1]); w.y = pk2e(o[2], o[3]);
;                         *(u32x2*)(ACT + ((size_t)b * SEQ + p - NMETA) * DFF + c4) = w; } }
.LBB0_914:
	s_or_b64 exec, exec, s[8:9]
	ds_read_b128 v[28:31], v97 offset:8720
	ds_read_b128 v[24:27], v98 offset:8208
	s_waitcnt lgkmcnt(0)
	v_mov_b32_dpp v28, v20 row_shr:1 row_mask:0xf bank_mask:0xf
	v_mov_b32_dpp v24, v20 row_shr:2 row_mask:0xf bank_mask:0xf
	v_mov_b32_dpp v29, v21 row_shr:1 row_mask:0xf bank_mask:0xf
	v_mov_b32_dpp v25, v21 row_shr:2 row_mask:0xf bank_mask:0xf
	v_mov_b32_dpp v30, v22 row_shr:1 row_mask:0xf bank_mask:0xf
	v_mov_b32_dpp v26, v22 row_shr:2 row_mask:0xf bank_mask:0xf
	v_mov_b32_dpp v31, v23 row_shr:1 row_mask:0xf bank_mask:0xf
	v_mov_b32_dpp v27, v23 row_shr:2 row_mask:0xf bank_mask:0xf
	s_and_saveexec_b64 s[8:9], s[38:39]
	s_cbranch_execz .LBB0_916
	v_pk_fma_f32 v[20:21], v[20:21], v[72:73], v[76:77]
	v_pk_fma_f32 v[22:23], v[22:23], v[74:75], v[78:79]
	v_pk_fma_f32 v[20:21], v[68:69], v[28:29], v[20:21]
	v_pk_fma_f32 v[22:23], v[70:71], v[30:31], v[22:23]
	v_pk_fma_f32 v[20:21], v[60:61], v[24:25], v[20:21]
	v_pk_fma_f32 v[22:23], v[62:63], v[26:27], v[22:23]
	v_pk_mul_f32 v[24:25], v[20:21], s[98:99] op_sel_hi:[1,0]
	v_pk_mul_f32 v[26:27], v[22:23], s[98:99] op_sel_hi:[1,0]
	v_pk_mul_f32 v[24:25], v[20:21], v[24:25]
	v_pk_mul_f32 v[26:27], v[22:23], v[26:27]
	v_pk_fma_f32 v[24:25], v[20:21], v[24:25], v[20:21]
	v_pk_fma_f32 v[26:27], v[22:23], v[26:27], v[22:23]
	v_pk_mul_f32 v[24:25], v[24:25], s[100:101] op_sel_hi:[1,0]
	v_pk_mul_f32 v[26:27], v[26:27], s[100:101] op_sel_hi:[1,0]
	v_exp_f32_e32 v24, v24
	v_exp_f32_e32 v25, v25
	v_exp_f32_e32 v26, v26
	v_exp_f32_e32 v27, v27
	v_pk_add_f32 v[24:25], v[24:25], 1.0 op_sel_hi:[1,0]
	v_pk_add_f32 v[26:27], v[26:27], 1.0 op_sel_hi:[1,0]
	v_rcp_f32_e32 v24, v24
	v_rcp_f32_e32 v25, v25
	v_rcp_f32_e32 v26, v26
	v_rcp_f32_e32 v27, v27
	s_nop 0
	v_pk_mul_f32 v[20:21], v[20:21], v[24:25]
	v_readlane_b32 s12, v237, 50
	v_pk_mul_f32 v[16:17], v[16:17], v[20:21]
	v_pk_mul_f32 v[20:21], v[22:23], v[26:27]
	v_readlane_b32 s13, v237, 51
	v_pk_mul_f32 v[18:19], v[18:19], v[20:21]
	v_cvt_pk_bf16_f32 v218, v16, v17
	v_cvt_pk_bf16_f32 v219, v18, v19
	v_mov_b64_e32 v[18:19], s[12:13]
	v_mad_u64_u32 v[18:19], s[26:27], v96, s66, v[18:19]
	v_lshl_add_u64 v[18:19], v[88:89], 1, v[18:19]
	v_add_co_u32_e32 v18, vcc, 0xfffea000, v18
	s_nop 1
	v_addc_co_u32_e32 v19, vcc, -1, v19, vcc
	global_store_dwordx4 v[18:19], v[216:219], off offset:-8
.LBB0_916:
	s_or_b64 exec, exec, s[8:9]
	ds_read_b128 v[20:23], v92 offset:9744
	ds_read_b128 v[16:19], v93 offset:9232
	s_waitcnt lgkmcnt(0)
	v_mov_b32_dpp v20, v12 row_shr:1 row_mask:0xf bank_mask:0xf
	v_mov_b32_dpp v16, v12 row_shr:2 row_mask:0xf bank_mask:0xf
	v_mov_b32_dpp v21, v13 row_shr:1 row_mask:0xf bank_mask:0xf
	v_mov_b32_dpp v17, v13 row_shr:2 row_mask:0xf bank_mask:0xf
	v_mov_b32_dpp v22, v14 row_shr:1 row_mask:0xf bank_mask:0xf
	v_mov_b32_dpp v18, v14 row_shr:2 row_mask:0xf bank_mask:0xf
	v_mov_b32_dpp v23, v15 row_shr:1 row_mask:0xf bank_mask:0xf
	v_mov_b32_dpp v19, v15 row_shr:2 row_mask:0xf bank_mask:0xf
	s_and_saveexec_b64 s[8:9], s[40:41]
	s_cbranch_execz .LBB0_918
	v_pk_fma_f32 v[12:13], v[12:13], v[72:73], v[76:77]
	v_pk_fma_f32 v[14:15], v[14:15], v[74:75], v[78:79]
	v_pk_fma_f32 v[12:13], v[68:69], v[20:21], v[12:13]
	v_pk_fma_f32 v[14:15], v[70:71], v[22:23], v[14:15]
	v_pk_fma_f32 v[12:13], v[60:61], v[16:17], v[12:13]
	v_pk_fma_f32 v[14:15], v[62:63], v[18:19], v[14:15]
	v_pk_mul_f32 v[16:17], v[12:13], s[98:99] op_sel_hi:[1,0]
	v_pk_mul_f32 v[18:19], v[14:15], s[98:99] op_sel_hi:[1,0]
	v_pk_mul_f32 v[16:17], v[12:13], v[16:17]
	v_pk_mul_f32 v[18:19], v[14:15], v[18:19]
	v_pk_fma_f32 v[16:17], v[12:13], v[16:17], v[12:13]
	v_pk_fma_f32 v[18:19], v[14:15], v[18:19], v[14:15]
	v_pk_mul_f32 v[16:17], v[16:17], s[100:101] op_sel_hi:[1,0]
	v_pk_mul_f32 v[18:19], v[18:19], s[100:101] op_sel_hi:[1,0]
	v_exp_f32_e32 v16, v16
	v_exp_f32_e32 v17, v17
	v_exp_f32_e32 v18, v18
	v_exp_f32_e32 v19, v19
	v_pk_add_f32 v[16:17], v[16:17], 1.0 op_sel_hi:[1,0]
	v_pk_add_f32 v[18:19], v[18:19], 1.0 op_sel_hi:[1,0]
	v_rcp_f32_e32 v16, v16
	v_rcp_f32_e32 v17, v17
	v_rcp_f32_e32 v18, v18
	v_rcp_f32_e32 v19, v19
	s_nop 0
	v_pk_mul_f32 v[12:13], v[12:13], v[16:17]
	v_readlane_b32 s12, v237, 50
	v_pk_mul_f32 v[8:9], v[8:9], v[12:13]
	v_pk_mul_f32 v[12:13], v[14:15], v[18:19]
	v_readlane_b32 s13, v237, 51
	v_pk_mul_f32 v[10:11], v[10:11], v[12:13]
	v_cvt_pk_bf16_f32 v230, v8, v9
	v_cvt_pk_bf16_f32 v231, v10, v11
	v_mov_b64_e32 v[10:11], s[12:13]
	v_mad_u64_u32 v[10:11], s[26:27], v90, s66, v[10:11]
	v_lshl_add_u64 v[10:11], v[88:89], 1, v[10:11]
	v_add_co_u32_e32 v10, vcc, 0xfffea000, v10
	s_nop 1
	v_addc_co_u32_e32 v11, vcc, -1, v11, vcc
	global_store_dwordx4 v[10:11], v[228:231], off offset:-8
.LBB0_918:
	s_or_b64 exec, exec, s[8:9]
	ds_read_b128 v[12:15], v94 offset:10768
	ds_read_b128 v[8:11], v95 offset:10256
	s_waitcnt lgkmcnt(0)
	v_mov_b32_dpp v12, v4 row_shr:1 row_mask:0xf bank_mask:0xf
	v_mov_b32_dpp v8, v4 row_shr:2 row_mask:0xf bank_mask:0xf
	v_mov_b32_dpp v13, v5 row_shr:1 row_mask:0xf bank_mask:0xf
	v_mov_b32_dpp v9, v5 row_shr:2 row_mask:0xf bank_mask:0xf
	v_mov_b32_dpp v14, v6 row_shr:1 row_mask:0xf bank_mask:0xf
	v_mov_b32_dpp v10, v6 row_shr:2 row_mask:0xf bank_mask:0xf
	v_mov_b32_dpp v15, v7 row_shr:1 row_mask:0xf bank_mask:0xf
	v_mov_b32_dpp v11, v7 row_shr:2 row_mask:0xf bank_mask:0xf
	s_and_saveexec_b64 s[8:9], s[6:7]
	s_cbranch_execz .LBB0_920
	v_pk_fma_f32 v[4:5], v[4:5], v[72:73], v[76:77]
	v_pk_fma_f32 v[6:7], v[6:7], v[74:75], v[78:79]
	v_pk_fma_f32 v[4:5], v[68:69], v[12:13], v[4:5]
	v_pk_fma_f32 v[6:7], v[70:71], v[14:15], v[6:7]
	v_pk_fma_f32 v[4:5], v[60:61], v[8:9], v[4:5]
	v_pk_fma_f32 v[6:7], v[62:63], v[10:11], v[6:7]
	v_pk_mul_f32 v[8:9], v[4:5], s[98:99] op_sel_hi:[1,0]
	v_pk_mul_f32 v[10:11], v[6:7], s[98:99] op_sel_hi:[1,0]
	v_pk_mul_f32 v[8:9], v[4:5], v[8:9]
	v_pk_mul_f32 v[10:11], v[6:7], v[10:11]
	v_pk_fma_f32 v[8:9], v[4:5], v[8:9], v[4:5]
	v_pk_fma_f32 v[10:11], v[6:7], v[10:11], v[6:7]
	v_pk_mul_f32 v[8:9], v[8:9], s[100:101] op_sel_hi:[1,0]
	v_pk_mul_f32 v[10:11], v[10:11], s[100:101] op_sel_hi:[1,0]
	v_exp_f32_e32 v8, v8
	v_exp_f32_e32 v9, v9
	v_exp_f32_e32 v10, v10
	v_exp_f32_e32 v11, v11
	v_pk_add_f32 v[8:9], v[8:9], 1.0 op_sel_hi:[1,0]
	v_pk_add_f32 v[10:11], v[10:11], 1.0 op_sel_hi:[1,0]
	v_rcp_f32_e32 v8, v8
	v_rcp_f32_e32 v9, v9
	v_rcp_f32_e32 v10, v10
	v_rcp_f32_e32 v11, v11
	s_nop 0
	v_pk_mul_f32 v[4:5], v[4:5], v[8:9]
	v_readlane_b32 s6, v237, 50
	v_pk_mul_f32 v[0:1], v[0:1], v[4:5]
	v_pk_mul_f32 v[4:5], v[6:7], v[10:11]
	v_readlane_b32 s7, v237, 51
	v_pk_mul_f32 v[2:3], v[2:3], v[4:5]
	v_cvt_pk_bf16_f32 v234, v0, v1
	v_cvt_pk_bf16_f32 v235, v2, v3
	v_mov_b64_e32 v[2:3], s[6:7]
	v_mad_u64_u32 v[2:3], s[6:7], v91, s66, v[2:3]
	v_lshl_add_u64 v[2:3], v[88:89], 1, v[2:3]
	v_add_co_u32_e32 v2, vcc, 0xfffea000, v2
	s_nop 1
	v_addc_co_u32_e32 v3, vcc, -1, v3, vcc
	global_store_dwordx4 v[2:3], v[232:235], off offset:-8
